# sample-attention units moved to the even workgroups (shorter prompt work) for balance
# baseline (speedup 1.0000x reference)
; #define LAS __attribute__((address_space(3)))
; __device__ __forceinline__ void attn_sample_unit(const Params& P, LAS unsigned char* lds, int li, int b, int h, const int tid) {
;     const int lane = tid & 63, wid = tid >> 6;
;     const bf16_t* QKV = (const bf16_t*)(P.ws + WS_R1); bf16_t* MIX = (bf16_t*)(P.ws + WS_MIX);
;     LAS float* qs = (LAS float*)lds;
;     LAS float* sc = qs + 1024;
;     LAS float* tab = sc + 16 * 528;
;     const size_t rb = (size_t)TP + b * SSEQ;
;     for (int i = tid; i < 1024; i += 512) qs[i] = bf2f(QKV[(rb + (i >> 6)) * NQKV + h * 64 + (i & 63)]);
; __global__ void __launch_bounds__(512, 2) hybrid_fwd(Params P) {
;     ...
;                     attn_build_bias(Q, lds, li, (wg >> 1) & 15, tid);
;                     for (int u = wg * 8; u < wg * 8 + 8; ++u) attn_prompt_unit(Q, lds, li, u >> 8, (u >> 4) & 15, u & 15, tid);
;                     if (wg < 128) attn_sample_unit(Q, lds, li, wg >> 4, wg & 15, tid);
.LBB0_87:
	v_readlane_b32 s22, v245, 51
	s_bitcmp0_b32 s94, 0
	v_readlane_b32 s23, v245, 52
	s_cbranch_scc0 .LBB0_122
	s_lshr_b32 s2, s94, 1
	s_and_b32 s2, s2, -16
	s_bfe_u32 s4, s94, 0x40001
	s_ashr_i32 s0, s2, 31
	s_add_u32 s18, s2, 0x8000
	s_addc_u32 s19, s0, 0
	s_movk_i32 s0, 0x400
	v_cmp_gt_i32_e32 vcc, s0, v166
	s_and_saveexec_b64 s[0:1], vcc
	s_movk_i32 s14, 0x1ff
	s_cbranch_execz .LBB0_100
	s_lshl_b32 s12, s4, 7
	v_max_i32_e32 v2, 0x200, v166
	s_add_u32 s12, s64, s12
	v_sub_u32_e32 v2, v2, v166
	s_addc_u32 s13, s65, 0
	v_lshlrev_b32_e32 v160, 1, v164
	v_add_u32_e32 v3, 0x1ff, v2
	v_lshl_add_u64 v[0:1], s[12:13], 0, v[160:161]
	v_cmp_lt_u32_e32 vcc, s14, v3
	s_mov_b64 s[34:35], -1
	v_mov_b32_e32 v2, v166
	s_and_saveexec_b64 s[28:29], vcc
	s_cbranch_execz .LBB0_97
	v_lshrrev_b32_e32 v4, 9, v3
	v_add_u32_e32 v167, 0x200, v166
	v_add_u32_e32 v5, -1, v4
	v_cmp_lt_u32_e32 vcc, 1, v5
	v_mov_b32_e32 v6, 0
	v_mov_b64_e32 v[2:3], v[166:167]
	s_and_saveexec_b64 s[34:35], vcc
	s_cbranch_execz .LBB0_94
	v_lshrrev_b32_e32 v2, 1, v5
	v_add_u32_e32 v2, 1, v2
	v_and_b32_e32 v6, -2, v2
	v_lshl_add_u32 v7, v166, 2, 0
	s_mov_b32 s12, 0
	s_mov_b64 s[38:39], 0
	v_mov_b64_e32 v[2:3], v[166:167]

; __device__ __forceinline__ void attn_sample_unit(const Params& P, LAS unsigned char* lds, int li, int b, int h, const int tid) {
;     ...
;     const float* kc = P.in[5] + ((size_t)(li * 8 + b) * 512) * 1024 + h * 64;
;     const float* vc = P.in[6] + ((size_t)(li * 8 + b) * 512) * 1024 + h * 64;
;     for (int j = tid; j < 528; j += 512) {
.LBB0_102:
	s_or_b64 exec, exec, s[0:1]
	s_ashr_i32 s0, s94, 5
	s_lshl_b32 s1, s16, 3
	s_add_i32 s0, s1, s0
	s_ashr_i32 s1, s0, 31
	s_movk_i32 s11, 0x210
	s_lshl_b64 s[0:1], s[0:1], 19
	s_lshl_b32 s4, s4, 6
	v_cmp_gt_i32_e32 vcc, s11, v166
	s_waitcnt lgkmcnt(0)
	s_barrier
	s_and_saveexec_b64 s[28:29], vcc
	s_cbranch_execz .LBB0_111
	v_readlane_b32 s40, v247, 9
	s_lshl_b64 s[12:13], s[0:1], 2
	v_readlane_b32 s50, v247, 19
	v_readlane_b32 s51, v247, 20
	s_add_u32 s11, s50, s12
	s_addc_u32 s12, s51, s13
	s_lshl_b32 s13, s4, 2
	s_add_u32 s38, s11, s13
	s_addc_u32 s39, s12, 0
	s_lshl_b32 s11, s4, 1
	v_readlane_b32 s41, v247, 10
	v_readlane_b32 s42, v247, 11
	v_readlane_b32 s43, v247, 12
	s_add_u32 s40, s64, s11
	s_addc_u32 s41, s65, 0
	s_waitcnt vmcnt(12)
	v_sub_u32_e32 v68, 0x200, v166
	v_lshl_add_u32 v69, v166, 2, v201
	s_mov_b64 s[42:43], 0
	v_mov_b32_e32 v64, v166
	v_readlane_b32 s44, v247, 13
	v_readlane_b32 s45, v247, 14
	v_readlane_b32 s46, v247, 15
	v_readlane_b32 s47, v247, 16
	v_readlane_b32 s48, v247, 17
	v_readlane_b32 s49, v247, 18
	v_readlane_b32 s52, v247, 21
	v_readlane_b32 s53, v247, 22
	v_readlane_b32 s54, v247, 23
	v_readlane_b32 s55, v247, 24
